# wt3_pz_ss + G1/G3 leading half issues its epilogue operand loads before the unit-end barrier
# speedup vs baseline: 1.0317x; 1.0140x over previous
.LBB0_322:
	s_add_u32 s4, s0, 0xfffc0080
	s_addc_u32 s5, s1, -1
	s_add_i32 s44, 0, 0x10000
	s_cmp_eq_u32 s93, 12
	s_cselect_b32 s71, s31, s5
	s_cselect_b32 s70, s39, s4
	s_cselect_b32 s69, s41, s92
	s_cselect_b32 s68, s40, s91
	s_add_i32 s4, 0, 0x14000
	v_add_u32_e32 v144, s44, v175
	v_add_u32_e32 v168, s4, v175
	ds_read_b128 v[132:135], v144
	ds_read_b128 v[136:139], v144 offset:1024
	ds_read_b128 v[140:143], v144 offset:2048
	ds_read_b128 v[144:147], v144 offset:3072
	ds_read_b128 v[156:159], v168
	ds_read_b128 v[160:163], v168 offset:1024
	ds_read_b128 v[164:167], v168 offset:2048
	ds_read_b128 v[180:183], v168 offset:3072
	s_add_i32 s94, s77, 0
	v_lshl_add_u64 v[168:169], s[0:1], 0, v[98:99]
	s_add_i32 m0, s94, 0xc000
	ds_read_b128 v[184:187], v179
	ds_read_b128 v[188:191], v179 offset:1024
	ds_read_b128 v[192:195], v179 offset:2048
	ds_read_b128 v[204:207], v179 offset:3072
	ds_read_b128 v[208:211], v179 offset:4096
	ds_read_b128 v[212:215], v179 offset:5120
	ds_read_b128 v[216:219], v179 offset:6144
	ds_read_b128 v[220:223], v179 offset:7168
	global_load_lds_dwordx4 v[168:169], off
	v_lshl_add_u64 v[168:169], s[0:1], 0, v[150:151]
	s_add_i32 m0, s94, 0xe000
	s_nop 0
	global_load_lds_dwordx4 v[168:169], off
	s_waitcnt vmcnt(8)
	s_waitcnt lgkmcnt(0)
	s_setprio 1
	s_barrier
	v_mfma_f32_16x16x32_bf16 v[128:131], v[132:135], v[184:187], v[128:131]
	v_mfma_f32_16x16x32_bf16 v[124:127], v[140:143], v[184:187], v[124:127]
	v_mfma_f32_16x16x32_bf16 v[120:123], v[132:135], v[192:195], v[120:123]
	v_mfma_f32_16x16x32_bf16 v[112:115], v[140:143], v[192:195], v[112:115]
	v_mfma_f32_16x16x32_bf16 v[104:107], v[132:135], v[208:211], v[104:107]
	v_mfma_f32_16x16x32_bf16 v[94:97], v[140:143], v[208:211], v[94:97]
	v_mfma_f32_16x16x32_bf16 v[86:89], v[132:135], v[216:219], v[86:89]
	v_mfma_f32_16x16x32_bf16 v[78:81], v[140:143], v[216:219], v[78:81]
	v_mfma_f32_16x16x32_bf16 v[128:131], v[136:139], v[188:191], v[128:131]
	v_mfma_f32_16x16x32_bf16 v[124:127], v[144:147], v[188:191], v[124:127]
	v_mfma_f32_16x16x32_bf16 v[120:123], v[136:139], v[204:207], v[120:123]
	v_mfma_f32_16x16x32_bf16 v[112:115], v[144:147], v[204:207], v[112:115]
	v_mfma_f32_16x16x32_bf16 v[104:107], v[136:139], v[212:215], v[104:107]
	v_mfma_f32_16x16x32_bf16 v[94:97], v[144:147], v[212:215], v[94:97]
	v_mfma_f32_16x16x32_bf16 v[86:89], v[136:139], v[220:223], v[86:89]
	v_mfma_f32_16x16x32_bf16 v[78:81], v[144:147], v[220:223], v[78:81]
	s_setprio 0
	s_setprio 1
	v_mfma_f32_16x16x32_bf16 v[116:119], v[156:159], v[184:187], v[116:119]
	v_mfma_f32_16x16x32_bf16 v[108:111], v[164:167], v[184:187], v[108:111]
	v_mfma_f32_16x16x32_bf16 v[100:103], v[156:159], v[192:195], v[100:103]
	v_mfma_f32_16x16x32_bf16 v[90:93], v[164:167], v[192:195], v[90:93]
	v_mfma_f32_16x16x32_bf16 v[82:85], v[156:159], v[208:211], v[82:85]
	v_mfma_f32_16x16x32_bf16 v[74:77], v[164:167], v[208:211], v[74:77]
	v_mfma_f32_16x16x32_bf16 v[70:73], v[156:159], v[216:219], v[70:73]
	v_mfma_f32_16x16x32_bf16 v[66:69], v[164:167], v[216:219], v[66:69]
	v_mfma_f32_16x16x32_bf16 v[116:119], v[160:163], v[188:191], v[116:119]
	v_mfma_f32_16x16x32_bf16 v[108:111], v[180:183], v[188:191], v[108:111]
	v_mfma_f32_16x16x32_bf16 v[100:103], v[160:163], v[204:207], v[100:103]
	v_mfma_f32_16x16x32_bf16 v[90:93], v[180:183], v[204:207], v[90:93]
	v_mfma_f32_16x16x32_bf16 v[82:85], v[160:163], v[212:215], v[82:85]
	v_mfma_f32_16x16x32_bf16 v[74:77], v[180:183], v[212:215], v[74:77]
	v_mfma_f32_16x16x32_bf16 v[70:73], v[160:163], v[220:223], v[70:73]
	v_mfma_f32_16x16x32_bf16 v[66:69], v[180:183], v[220:223], v[66:69]
	s_setprio 0
	s_barrier
	s_add_i32 s5, s44, s77
	v_lshl_add_u64 v[168:169], s[68:69], 0, v[148:149]
	s_mov_b32 m0, s5
	ds_read_b128 v[184:187], v179 offset:16384
	ds_read_b128 v[188:191], v179 offset:17408
	ds_read_b128 v[192:195], v179 offset:18432
	ds_read_b128 v[204:207], v179 offset:19456
	ds_read_b128 v[208:211], v179 offset:20480
	ds_read_b128 v[212:215], v179 offset:21504
	ds_read_b128 v[216:219], v179 offset:22528
	ds_read_b128 v[220:223], v179 offset:23552
	global_load_lds_dwordx4 v[168:169], off
	s_add_i32 m0, s5, 0x2000
	s_add_u32 s44, s68, 0x40000
	v_lshl_add_u64 v[172:173], s[68:69], 0, v[152:153]
	s_addc_u32 s45, s69, 0
	s_add_i32 s4, s4, s77
	global_load_lds_dwordx4 v[172:173], off
	v_lshl_add_u64 v[176:177], s[44:45], 0, v[148:149]
	s_mov_b32 m0, s4
	v_lshl_add_u64 v[200:201], s[70:71], 0, v[150:151]
	global_load_lds_dwordx4 v[176:177], off
	v_lshl_add_u64 v[176:177], s[44:45], 0, v[152:153]
	s_add_i32 m0, s4, 0x2000
	s_nop 0
	global_load_lds_dwordx4 v[176:177], off
	v_lshl_add_u64 v[176:177], s[70:71], 0, v[98:99]
	s_mov_b32 m0, s94
	s_nop 0
	global_load_lds_dwordx4 v[176:177], off
	s_add_i32 m0, s94, 0x2000
	s_nop 0
	global_load_lds_dwordx4 v[200:201], off
	s_waitcnt vmcnt(8)
	s_waitcnt lgkmcnt(0)
	s_setprio 1
	s_barrier
	v_mfma_f32_16x16x32_bf16 v[62:65], v[132:135], v[184:187], v[62:65]
	v_mfma_f32_16x16x32_bf16 v[58:61], v[140:143], v[184:187], v[58:61]
	v_mfma_f32_16x16x32_bf16 v[54:57], v[132:135], v[192:195], v[54:57]
	v_mfma_f32_16x16x32_bf16 v[46:49], v[140:143], v[192:195], v[46:49]
	v_mfma_f32_16x16x32_bf16 v[38:41], v[132:135], v[208:211], v[38:41]
	v_mfma_f32_16x16x32_bf16 v[30:33], v[140:143], v[208:211], v[30:33]
	v_mfma_f32_16x16x32_bf16 v[22:25], v[132:135], v[216:219], v[22:25]
	v_mfma_f32_16x16x32_bf16 v[14:17], v[140:143], v[216:219], v[14:17]
	v_mfma_f32_16x16x32_bf16 v[62:65], v[136:139], v[188:191], v[62:65]
	v_mfma_f32_16x16x32_bf16 v[58:61], v[144:147], v[188:191], v[58:61]
	v_mfma_f32_16x16x32_bf16 v[54:57], v[136:139], v[204:207], v[54:57]
	v_mfma_f32_16x16x32_bf16 v[46:49], v[144:147], v[204:207], v[46:49]
	v_mfma_f32_16x16x32_bf16 v[38:41], v[136:139], v[212:215], v[38:41]
	v_mfma_f32_16x16x32_bf16 v[30:33], v[144:147], v[212:215], v[30:33]
	v_mfma_f32_16x16x32_bf16 v[22:25], v[136:139], v[220:223], v[22:25]
	v_mfma_f32_16x16x32_bf16 v[14:17], v[144:147], v[220:223], v[14:17]
	s_setprio 0
	s_setprio 1
	v_mfma_f32_16x16x32_bf16 v[50:53], v[156:159], v[184:187], v[50:53]
	v_mfma_f32_16x16x32_bf16 v[42:45], v[164:167], v[184:187], v[42:45]
	v_mfma_f32_16x16x32_bf16 v[34:37], v[156:159], v[192:195], v[34:37]
	v_mfma_f32_16x16x32_bf16 v[26:29], v[164:167], v[192:195], v[26:29]
	v_mfma_f32_16x16x32_bf16 v[18:21], v[156:159], v[208:211], v[18:21]
	v_mfma_f32_16x16x32_bf16 v[10:13], v[164:167], v[208:211], v[10:13]
	v_mfma_f32_16x16x32_bf16 v[6:9], v[156:159], v[216:219], v[6:9]
	v_mfma_f32_16x16x32_bf16 v[2:5], v[164:167], v[216:219], v[2:5]
	v_mfma_f32_16x16x32_bf16 v[50:53], v[160:163], v[188:191], v[50:53]
	v_mfma_f32_16x16x32_bf16 v[42:45], v[180:183], v[188:191], v[42:45]
	v_mfma_f32_16x16x32_bf16 v[34:37], v[160:163], v[204:207], v[34:37]
	v_mfma_f32_16x16x32_bf16 v[26:29], v[180:183], v[204:207], v[26:29]
	v_mfma_f32_16x16x32_bf16 v[18:21], v[160:163], v[212:215], v[18:21]
	v_mfma_f32_16x16x32_bf16 v[10:13], v[180:183], v[212:215], v[10:13]
	v_mfma_f32_16x16x32_bf16 v[6:9], v[160:163], v[220:223], v[6:9]
	v_mfma_f32_16x16x32_bf16 v[2:5], v[180:183], v[220:223], v[2:5]
	s_setprio 0
	s_barrier
	s_add_i32 s4, 0, 0x18000
	s_add_i32 s5, 0, 0x1c000
	v_add_u32_e32 v144, s4, v175
	v_add_u32_e32 v170, s5, v175
	ds_read_b128 v[132:135], v144
	ds_read_b128 v[136:139], v144 offset:1024
	ds_read_b128 v[140:143], v144 offset:2048
	ds_read_b128 v[144:147], v144 offset:3072
	ds_read_b128 v[156:159], v170
	ds_read_b128 v[160:163], v170 offset:1024
	ds_read_b128 v[164:167], v170 offset:2048
	ds_read_b128 v[180:183], v170 offset:3072
	s_add_u32 s44, s70, 0x40000
	s_addc_u32 s45, s71, 0
	v_lshl_add_u64 v[202:203], s[44:45], 0, v[98:99]
	s_add_i32 m0, s94, 0x4000
	ds_read_b128 v[184:187], v179 offset:32768
	ds_read_b128 v[188:191], v179 offset:33792
	ds_read_b128 v[192:195], v179 offset:34816
	ds_read_b128 v[204:207], v179 offset:35840
	ds_read_b128 v[208:211], v179 offset:36864
	ds_read_b128 v[212:215], v179 offset:37888
	ds_read_b128 v[216:219], v179 offset:38912
	ds_read_b128 v[220:223], v179 offset:39936
	global_load_lds_dwordx4 v[202:203], off
	v_lshl_add_u64 v[202:203], s[44:45], 0, v[150:151]
	s_add_i32 m0, s94, 0x6000
	s_nop 0
	global_load_lds_dwordx4 v[202:203], off
	s_waitcnt vmcnt(8)
	s_waitcnt lgkmcnt(0)
	s_setprio 1
	s_barrier
	v_mfma_f32_16x16x32_bf16 v[128:131], v[132:135], v[184:187], v[128:131]
	v_mfma_f32_16x16x32_bf16 v[124:127], v[140:143], v[184:187], v[124:127]
	v_mfma_f32_16x16x32_bf16 v[120:123], v[132:135], v[192:195], v[120:123]
	v_mfma_f32_16x16x32_bf16 v[112:115], v[140:143], v[192:195], v[112:115]
	v_mfma_f32_16x16x32_bf16 v[104:107], v[132:135], v[208:211], v[104:107]
	v_mfma_f32_16x16x32_bf16 v[94:97], v[140:143], v[208:211], v[94:97]
	v_mfma_f32_16x16x32_bf16 v[86:89], v[132:135], v[216:219], v[86:89]
	v_mfma_f32_16x16x32_bf16 v[78:81], v[140:143], v[216:219], v[78:81]
	v_mfma_f32_16x16x32_bf16 v[128:131], v[136:139], v[188:191], v[128:131]
	v_mfma_f32_16x16x32_bf16 v[124:127], v[144:147], v[188:191], v[124:127]
	v_mfma_f32_16x16x32_bf16 v[120:123], v[136:139], v[204:207], v[120:123]
	v_mfma_f32_16x16x32_bf16 v[112:115], v[144:147], v[204:207], v[112:115]
	v_mfma_f32_16x16x32_bf16 v[104:107], v[136:139], v[212:215], v[104:107]
	v_mfma_f32_16x16x32_bf16 v[94:97], v[144:147], v[212:215], v[94:97]
	v_mfma_f32_16x16x32_bf16 v[86:89], v[136:139], v[220:223], v[86:89]
	v_mfma_f32_16x16x32_bf16 v[78:81], v[144:147], v[220:223], v[78:81]
	s_setprio 0
	s_setprio 1
	v_mfma_f32_16x16x32_bf16 v[116:119], v[156:159], v[184:187], v[116:119]
	v_mfma_f32_16x16x32_bf16 v[108:111], v[164:167], v[184:187], v[108:111]
	v_mfma_f32_16x16x32_bf16 v[100:103], v[156:159], v[192:195], v[100:103]
	v_mfma_f32_16x16x32_bf16 v[90:93], v[164:167], v[192:195], v[90:93]
	v_mfma_f32_16x16x32_bf16 v[82:85], v[156:159], v[208:211], v[82:85]
	v_mfma_f32_16x16x32_bf16 v[74:77], v[164:167], v[208:211], v[74:77]
	v_mfma_f32_16x16x32_bf16 v[70:73], v[156:159], v[216:219], v[70:73]
	v_mfma_f32_16x16x32_bf16 v[66:69], v[164:167], v[216:219], v[66:69]
	v_mfma_f32_16x16x32_bf16 v[116:119], v[160:163], v[188:191], v[116:119]
	v_mfma_f32_16x16x32_bf16 v[108:111], v[180:183], v[188:191], v[108:111]
	v_mfma_f32_16x16x32_bf16 v[100:103], v[160:163], v[204:207], v[100:103]
	v_mfma_f32_16x16x32_bf16 v[90:93], v[180:183], v[204:207], v[90:93]
	v_mfma_f32_16x16x32_bf16 v[82:85], v[160:163], v[212:215], v[82:85]
	v_mfma_f32_16x16x32_bf16 v[74:77], v[180:183], v[212:215], v[74:77]
	v_mfma_f32_16x16x32_bf16 v[70:73], v[160:163], v[220:223], v[70:73]
	v_mfma_f32_16x16x32_bf16 v[66:69], v[180:183], v[220:223], v[66:69]
	s_setprio 0
	s_barrier
	s_add_i32 s4, s4, s77
	v_lshl_add_u64 v[168:169], v[168:169], 0, s[42:43]
	s_mov_b32 m0, s4
	ds_read_b128 v[184:187], v179 offset:49152
	ds_read_b128 v[188:191], v179 offset:50176
	ds_read_b128 v[192:195], v179 offset:51200
	ds_read_b128 v[204:207], v179 offset:52224
	ds_read_b128 v[208:211], v179 offset:53248
	ds_read_b128 v[212:215], v179 offset:54272
	ds_read_b128 v[216:219], v179 offset:55296
	ds_read_b128 v[220:223], v179 offset:56320
	global_load_lds_dwordx4 v[168:169], off
	s_add_i32 m0, s4, 0x2000
	s_add_u32 s44, s68, 0x40080
	v_lshl_add_u64 v[168:169], v[172:173], 0, s[42:43]
	s_addc_u32 s45, s69, 0
	s_add_i32 s4, s5, s77
	global_load_lds_dwordx4 v[168:169], off
	v_lshl_add_u64 v[168:169], s[44:45], 0, v[148:149]
	s_mov_b32 m0, s4
	s_nop 0
	global_load_lds_dwordx4 v[168:169], off
	v_lshl_add_u64 v[168:169], s[44:45], 0, v[152:153]
	s_add_i32 m0, s4, 0x2000
	s_nop 0
	global_load_lds_dwordx4 v[168:169], off
	v_lshl_add_u64 v[168:169], v[176:177], 0, s[42:43]
	s_add_i32 m0, s94, 0x8000
	s_nop 0
	global_load_lds_dwordx4 v[168:169], off
	v_lshl_add_u64 v[168:169], v[200:201], 0, s[42:43]
	s_add_i32 m0, s94, 0xa000
	s_nop 0
	global_load_lds_dwordx4 v[168:169], off
	s_waitcnt vmcnt(8)
	s_waitcnt lgkmcnt(0)
	s_setprio 1
	s_barrier
	v_mfma_f32_16x16x32_bf16 v[62:65], v[132:135], v[184:187], v[62:65]
	v_mfma_f32_16x16x32_bf16 v[58:61], v[140:143], v[184:187], v[58:61]
	v_mfma_f32_16x16x32_bf16 v[54:57], v[132:135], v[192:195], v[54:57]
	v_mfma_f32_16x16x32_bf16 v[46:49], v[140:143], v[192:195], v[46:49]
	v_mfma_f32_16x16x32_bf16 v[38:41], v[132:135], v[208:211], v[38:41]
	v_mfma_f32_16x16x32_bf16 v[30:33], v[140:143], v[208:211], v[30:33]
	v_mfma_f32_16x16x32_bf16 v[22:25], v[132:135], v[216:219], v[22:25]
	v_mfma_f32_16x16x32_bf16 v[14:17], v[140:143], v[216:219], v[14:17]
	v_mfma_f32_16x16x32_bf16 v[62:65], v[136:139], v[188:191], v[62:65]
	v_mfma_f32_16x16x32_bf16 v[58:61], v[144:147], v[188:191], v[58:61]
	v_mfma_f32_16x16x32_bf16 v[54:57], v[136:139], v[204:207], v[54:57]
	v_mfma_f32_16x16x32_bf16 v[46:49], v[144:147], v[204:207], v[46:49]
	v_mfma_f32_16x16x32_bf16 v[38:41], v[136:139], v[212:215], v[38:41]
	v_mfma_f32_16x16x32_bf16 v[30:33], v[144:147], v[212:215], v[30:33]
	v_mfma_f32_16x16x32_bf16 v[22:25], v[136:139], v[220:223], v[22:25]
	v_mfma_f32_16x16x32_bf16 v[14:17], v[144:147], v[220:223], v[14:17]
	s_setprio 0
	s_setprio 1
	v_mfma_f32_16x16x32_bf16 v[50:53], v[156:159], v[184:187], v[50:53]
	v_mfma_f32_16x16x32_bf16 v[42:45], v[164:167], v[184:187], v[42:45]
	v_mfma_f32_16x16x32_bf16 v[34:37], v[156:159], v[192:195], v[34:37]
	v_mfma_f32_16x16x32_bf16 v[26:29], v[164:167], v[192:195], v[26:29]
	v_mfma_f32_16x16x32_bf16 v[18:21], v[156:159], v[208:211], v[18:21]
	v_mfma_f32_16x16x32_bf16 v[10:13], v[164:167], v[208:211], v[10:13]
	v_mfma_f32_16x16x32_bf16 v[6:9], v[156:159], v[216:219], v[6:9]
	v_mfma_f32_16x16x32_bf16 v[2:5], v[164:167], v[216:219], v[2:5]
	v_mfma_f32_16x16x32_bf16 v[50:53], v[160:163], v[188:191], v[50:53]
	v_mfma_f32_16x16x32_bf16 v[42:45], v[180:183], v[188:191], v[42:45]
	v_mfma_f32_16x16x32_bf16 v[34:37], v[160:163], v[204:207], v[34:37]
	v_mfma_f32_16x16x32_bf16 v[26:29], v[180:183], v[204:207], v[26:29]
	v_mfma_f32_16x16x32_bf16 v[18:21], v[160:163], v[212:215], v[18:21]
	v_mfma_f32_16x16x32_bf16 v[10:13], v[180:183], v[212:215], v[10:13]
	v_mfma_f32_16x16x32_bf16 v[6:9], v[160:163], v[220:223], v[6:9]
	v_mfma_f32_16x16x32_bf16 v[2:5], v[180:183], v[220:223], v[2:5]
	s_setprio 0
	s_barrier
	s_add_i32 s93, s93, 2
	s_add_u32 s0, s0, 0x100
	s_addc_u32 s1, s1, 0
	s_add_u32 s91, s91, 0x100
	s_addc_u32 s92, s92, 0
	s_cmp_gt_u32 s93, 13
	s_cbranch_scc0 .LBB0_322
	s_mov_b32 s100, 1
	s_and_b64 vcc, exec, s[14:15]
	s_cbranch_vccz .LBB0_325
	s_lshl_b32 s0, s89, 8
	v_add_u32_e32 v176, s0, v171
	v_ashrrev_i32_e32 v177, 31, v176
	v_or_b32_e32 v172, 16, v176
	v_lshlrev_b64 v[132:133], 6, v[176:177]
	v_ashrrev_i32_e32 v173, 31, v172
	v_or_b32_e32 v168, 32, v176
	v_lshl_add_u64 v[132:133], v[154:155], 0, v[132:133]
	v_lshlrev_b64 v[134:135], 6, v[172:173]
	v_ashrrev_i32_e32 v169, 31, v168
	v_lshl_add_u64 v[134:135], v[154:155], 0, v[134:135]
	global_load_dwordx4 v[180:183], v[132:133], off
	global_load_dwordx4 v[184:187], v[134:135], off
	v_lshlrev_b64 v[132:133], 6, v[168:169]
	v_lshl_add_u64 v[132:133], v[154:155], 0, v[132:133]
	global_load_dwordx4 v[188:191], v[132:133], off
	v_or_b32_e32 v166, 48, v176
	v_ashrrev_i32_e32 v167, 31, v166
	v_lshlrev_b64 v[132:133], 6, v[166:167]
	v_lshl_add_u64 v[132:133], v[154:155], 0, v[132:133]
	global_load_dwordx4 v[192:195], v[132:133], off
	v_add_u32_e32 v162, 0x80, v176
	v_ashrrev_i32_e32 v163, 31, v162
	v_lshlrev_b64 v[132:133], 6, v[162:163]
	v_lshl_add_u64 v[132:133], v[154:155], 0, v[132:133]
	global_load_dwordx4 v[204:207], v[132:133], off
	s_addk_i32 s0, 0xc000
	s_lshr_b32 s0, s0, 12
	v_add_u32_e32 v164, 0x90, v176
	s_ashr_i32 s1, s89, 5
	v_and_b32_e32 v132, 64, v229
	v_ashrrev_i32_e32 v165, 31, v164
	s_add_i32 s0, s0, 2
	v_add_u32_e32 v136, 64, v132
	v_lshlrev_b64 v[132:133], 6, v[164:165]
	v_add_u32_e32 v160, 0xa0, v176
	s_cmp_lt_i32 s89, 64
	v_lshl_add_u64 v[132:133], v[154:155], 0, v[132:133]
	v_ashrrev_i32_e32 v161, 31, v160
	s_cselect_b32 s0, s1, s0
	v_xor_b32_e32 v134, 16, v229
	global_load_dwordx4 v[208:211], v[132:133], off
	v_add_u32_e32 v158, 0xb0, v176
	v_lshlrev_b64 v[132:133], 6, v[160:161]
	s_mul_hi_i32 s1, s0, 0x1800
	s_mulk_i32 s0, 0x1800
	v_lshl_or_b32 v156, s90, 8, v178
	v_xor_b32_e32 v135, 32, v229
	v_cmp_lt_i32_e32 vcc, v134, v136
	v_ashrrev_i32_e32 v159, 31, v158
	v_lshl_add_u64 v[132:133], v[154:155], 0, v[132:133]
	s_add_u32 s0, s78, s0
	v_ashrrev_i32_e32 v157, 31, v156
	v_cndmask_b32_e32 v134, v229, v134, vcc
	v_cmp_lt_i32_e32 vcc, v135, v136
	global_load_dwordx4 v[212:215], v[132:133], off
	v_lshlrev_b64 v[132:133], 6, v[158:159]
	s_addc_u32 s1, s79, s1
	v_cndmask_b32_e32 v135, v229, v135, vcc
	v_lshl_add_u64 v[132:133], v[154:155], 0, v[132:133]
	v_lshl_add_u64 v[136:137], v[156:157], 2, s[0:1]
	v_lshlrev_b32_e32 v161, 2, v134
	v_lshlrev_b32_e32 v163, 2, v135
	global_load_dwordx4 v[216:219], v[132:133], off
	global_load_dwordx4 v[140:143], v[136:137], off offset:16
	global_load_dwordx4 v[144:147], v[136:137], off
	s_nop 0
	global_load_dwordx4 v[132:135], v[136:137], off offset:528
	s_nop 0
	global_load_dwordx4 v[136:139], v[136:137], off offset:512
	s_barrier
	s_branch .Lmy_g1_afterload

.Lmy_g1_afterload:
	s_and_b64 vcc, exec, s[36:37]
	s_waitcnt vmcnt(0)
	v_mov_b32_e32 v200, v181
	v_mov_b32_e32 v201, v182
	v_mov_b32_e32 v181, v183
	v_pk_add_f32 v[180:181], v[200:201], v[180:181]
	v_mov_b32_e32 v182, v185
	v_mov_b32_e32 v183, v186
	v_mov_b32_e32 v185, v187
	v_add_f32_e32 v159, v180, v181
	v_pk_add_f32 v[180:181], v[182:183], v[184:185]
	v_mov_b32_e32 v186, v189
	v_mov_b32_e32 v187, v190
	v_mov_b32_e32 v189, v191
	ds_bpermute_b32 v165, v161, v159
	v_add_f32_e32 v167, v180, v181
	v_pk_add_f32 v[182:183], v[186:187], v[188:189]
	ds_bpermute_b32 v173, v161, v167
	v_add_f32_e32 v169, v182, v183
	ds_bpermute_b32 v174, v161, v169
	s_waitcnt lgkmcnt(2)
	v_add_f32_e32 v159, v159, v165
	v_mov_b32_e32 v190, v193
	v_mov_b32_e32 v191, v194
	v_mov_b32_e32 v193, v195
	ds_bpermute_b32 v165, v163, v159
	s_waitcnt lgkmcnt(2)
	v_add_f32_e32 v167, v167, v173
	v_pk_add_f32 v[184:185], v[190:191], v[192:193]
	ds_bpermute_b32 v173, v163, v167
	v_add_f32_e32 v170, v184, v185
	s_waitcnt lgkmcnt(2)
	v_add_f32_e32 v169, v169, v174
	ds_bpermute_b32 v177, v161, v170
	ds_bpermute_b32 v174, v163, v169
	s_waitcnt lgkmcnt(3)
	v_add_f32_e32 v159, v159, v165
	v_fmamk_f32 v159, v159, 0x3a800000, v1
	s_waitcnt lgkmcnt(2)
	v_add_f32_e32 v165, v167, v173
	v_mov_b32_e32 v184, v205
	v_mov_b32_e32 v185, v206
	v_mov_b32_e32 v205, v207
	v_rsq_f32_e32 v180, v159
	v_fmamk_f32 v159, v165, 0x3a800000, v1
	v_pk_add_f32 v[184:185], v[184:185], v[204:205]
	v_rsq_f32_e32 v182, v159
	s_waitcnt lgkmcnt(0)
	v_add_f32_e32 v159, v169, v174
	v_add_f32_e32 v165, v170, v177
	v_add_f32_e32 v169, v184, v185
	ds_bpermute_b32 v167, v163, v165
	ds_bpermute_b32 v170, v161, v169
	v_fmamk_f32 v159, v159, 0x3a800000, v1
	v_rsq_f32_e32 v184, v159
	v_mov_b32_e32 v186, v209
	s_waitcnt lgkmcnt(1)
	v_add_f32_e32 v159, v165, v167
	s_waitcnt lgkmcnt(0)
	v_add_f32_e32 v165, v169, v170
	v_mov_b32_e32 v187, v210
	v_mov_b32_e32 v209, v211
	ds_bpermute_b32 v167, v163, v165
	v_pk_add_f32 v[186:187], v[186:187], v[208:209]
	v_mad_i64_i32 v[176:177], s[0:1], v176, s29, v[156:157]
	v_add_f32_e32 v169, v186, v187
	v_pk_fma_f32 v[130:131], v[130:131], v[180:181], v[146:147] op_sel_hi:[1,0,1]
	v_pk_fma_f32 v[128:129], v[128:129], v[180:181], v[144:145] op_sel_hi:[1,0,1]
	v_pk_fma_f32 v[192:193], v[126:127], v[180:181], v[142:143] op_sel_hi:[1,0,1]
	v_pk_fma_f32 v[126:127], v[124:125], v[180:181], v[140:141] op_sel_hi:[1,0,1]
	ds_bpermute_b32 v170, v161, v169
	v_cvt_pk_bf16_f32 v124, v128, v129
	v_cvt_pk_bf16_f32 v125, v130, v131
	v_cvt_pk_bf16_f32 v126, v126, v127
	v_cvt_pk_bf16_f32 v127, v192, v193
	v_lshl_add_u64 v[128:129], v[176:177], 1, s[24:25]
	s_cbranch_vccz .Lmy_wt_g1_0
	global_store_dwordx4 v[128:129], v[124:127], off

.LBB0_1011:
	s_add_u32 s4, s40, 0xfffc0080
	s_addc_u32 s5, s41, -1
	s_add_i32 s6, 0, 0x10000
	s_cmp_eq_u32 s92, 12
	s_cselect_b32 s69, s21, s5
	s_cselect_b32 s68, s88, s4
	s_cselect_b32 s57, s15, s91
	s_cselect_b32 s56, s89, s90
	s_add_i32 s7, 0, 0x14000
	v_add_u32_e32 v144, s6, v189
	v_add_u32_e32 v160, s7, v189
	ds_read_b128 v[132:135], v144
	ds_read_b128 v[136:139], v144 offset:1024
	ds_read_b128 v[140:143], v144 offset:2048
	ds_read_b128 v[144:147], v144 offset:3072
	ds_read_b128 v[156:159], v160
	ds_read_b128 v[162:165], v160 offset:1024
	ds_read_b128 v[192:195], v160 offset:2048
	ds_read_b128 v[200:203], v160 offset:3072
	s_add_i32 s44, s70, 0
	v_lshl_add_u64 v[166:167], s[40:41], 0, v[98:99]
	s_add_i32 m0, s44, 0xc000
	ds_read_b128 v[204:207], v191
	ds_read_b128 v[208:211], v191 offset:1024
	ds_read_b128 v[212:215], v191 offset:2048
	ds_read_b128 v[216:219], v191 offset:3072
	ds_read_b128 v[220:223], v191 offset:4096
	ds_read_b128 v[224:227], v191 offset:5120
	ds_read_b128 v[238:241], v191 offset:6144
	ds_read_b128 v[242:245], v191 offset:7168
	global_load_lds_dwordx4 v[166:167], off
	v_lshl_add_u64 v[166:167], s[40:41], 0, v[150:151]
	s_add_i32 m0, s44, 0xe000
	s_nop 0
	global_load_lds_dwordx4 v[166:167], off
	s_waitcnt vmcnt(8)
	s_waitcnt lgkmcnt(0)
	s_setprio 1
	s_barrier
	v_mfma_f32_16x16x32_bf16 v[128:131], v[132:135], v[204:207], v[128:131]
	v_mfma_f32_16x16x32_bf16 v[124:127], v[140:143], v[204:207], v[124:127]
	v_mfma_f32_16x16x32_bf16 v[112:115], v[132:135], v[212:215], v[112:115]
	v_mfma_f32_16x16x32_bf16 v[108:111], v[140:143], v[212:215], v[108:111]
	v_mfma_f32_16x16x32_bf16 v[94:97], v[132:135], v[220:223], v[94:97]
	v_mfma_f32_16x16x32_bf16 v[90:93], v[140:143], v[220:223], v[90:93]
	v_mfma_f32_16x16x32_bf16 v[78:81], v[132:135], v[238:241], v[78:81]
	v_mfma_f32_16x16x32_bf16 v[74:77], v[140:143], v[238:241], v[74:77]
	v_mfma_f32_16x16x32_bf16 v[128:131], v[136:139], v[208:211], v[128:131]
	v_mfma_f32_16x16x32_bf16 v[124:127], v[144:147], v[208:211], v[124:127]
	v_mfma_f32_16x16x32_bf16 v[112:115], v[136:139], v[216:219], v[112:115]
	v_mfma_f32_16x16x32_bf16 v[108:111], v[144:147], v[216:219], v[108:111]
	v_mfma_f32_16x16x32_bf16 v[94:97], v[136:139], v[224:227], v[94:97]
	v_mfma_f32_16x16x32_bf16 v[90:93], v[144:147], v[224:227], v[90:93]
	v_mfma_f32_16x16x32_bf16 v[78:81], v[136:139], v[242:245], v[78:81]
	v_mfma_f32_16x16x32_bf16 v[74:77], v[144:147], v[242:245], v[74:77]
	s_setprio 0
	s_setprio 1
	v_mfma_f32_16x16x32_bf16 v[120:123], v[156:159], v[204:207], v[120:123]
	v_mfma_f32_16x16x32_bf16 v[116:119], v[192:195], v[204:207], v[116:119]
	v_mfma_f32_16x16x32_bf16 v[104:107], v[156:159], v[212:215], v[104:107]
	v_mfma_f32_16x16x32_bf16 v[100:103], v[192:195], v[212:215], v[100:103]
	v_mfma_f32_16x16x32_bf16 v[86:89], v[156:159], v[220:223], v[86:89]
	v_mfma_f32_16x16x32_bf16 v[82:85], v[192:195], v[220:223], v[82:85]
	v_mfma_f32_16x16x32_bf16 v[70:73], v[156:159], v[238:241], v[70:73]
	v_mfma_f32_16x16x32_bf16 v[66:69], v[192:195], v[238:241], v[66:69]
	v_mfma_f32_16x16x32_bf16 v[120:123], v[162:165], v[208:211], v[120:123]
	v_mfma_f32_16x16x32_bf16 v[116:119], v[200:203], v[208:211], v[116:119]
	v_mfma_f32_16x16x32_bf16 v[104:107], v[162:165], v[216:219], v[104:107]
	v_mfma_f32_16x16x32_bf16 v[100:103], v[200:203], v[216:219], v[100:103]
	v_mfma_f32_16x16x32_bf16 v[86:89], v[162:165], v[224:227], v[86:89]
	v_mfma_f32_16x16x32_bf16 v[82:85], v[200:203], v[224:227], v[82:85]
	v_mfma_f32_16x16x32_bf16 v[70:73], v[162:165], v[242:245], v[70:73]
	v_mfma_f32_16x16x32_bf16 v[66:69], v[200:203], v[242:245], v[66:69]
	s_setprio 0
	s_barrier
	s_add_i32 s4, s6, s70
	v_lshl_add_u64 v[166:167], s[56:57], 0, v[148:149]
	s_mov_b32 m0, s4
	ds_read_b128 v[204:207], v191 offset:16384
	ds_read_b128 v[208:211], v191 offset:17408
	ds_read_b128 v[212:215], v191 offset:18432
	ds_read_b128 v[216:219], v191 offset:19456
	ds_read_b128 v[220:223], v191 offset:20480
	ds_read_b128 v[224:227], v191 offset:21504
	ds_read_b128 v[238:241], v191 offset:22528
	ds_read_b128 v[242:245], v191 offset:23552
	global_load_lds_dwordx4 v[166:167], off
	s_add_i32 m0, s4, 0x2000
	s_add_u32 s4, s56, 0x40000
	v_lshl_add_u64 v[170:171], s[56:57], 0, v[152:153]
	s_addc_u32 s5, s57, 0
	s_add_i32 s6, s7, s70
	global_load_lds_dwordx4 v[170:171], off
	v_lshl_add_u64 v[176:177], s[4:5], 0, v[148:149]
	s_mov_b32 m0, s6
	v_lshl_add_u64 v[180:181], s[68:69], 0, v[150:151]
	global_load_lds_dwordx4 v[176:177], off
	v_lshl_add_u64 v[176:177], s[4:5], 0, v[152:153]
	s_add_i32 m0, s6, 0x2000
	s_nop 0
	global_load_lds_dwordx4 v[176:177], off
	v_lshl_add_u64 v[176:177], s[68:69], 0, v[98:99]
	s_mov_b32 m0, s44
	s_nop 0
	global_load_lds_dwordx4 v[176:177], off
	s_add_i32 m0, s44, 0x2000
	s_nop 0
	global_load_lds_dwordx4 v[180:181], off
	s_waitcnt vmcnt(8)
	s_waitcnt lgkmcnt(0)
	s_setprio 1
	s_barrier
	v_mfma_f32_16x16x32_bf16 v[62:65], v[132:135], v[204:207], v[62:65]
	v_mfma_f32_16x16x32_bf16 v[58:61], v[140:143], v[204:207], v[58:61]
	v_mfma_f32_16x16x32_bf16 v[46:49], v[132:135], v[212:215], v[46:49]
	v_mfma_f32_16x16x32_bf16 v[42:45], v[140:143], v[212:215], v[42:45]
	v_mfma_f32_16x16x32_bf16 v[30:33], v[132:135], v[220:223], v[30:33]
	v_mfma_f32_16x16x32_bf16 v[26:29], v[140:143], v[220:223], v[26:29]
	v_mfma_f32_16x16x32_bf16 v[14:17], v[132:135], v[238:241], v[14:17]
	v_mfma_f32_16x16x32_bf16 v[10:13], v[140:143], v[238:241], v[10:13]
	v_mfma_f32_16x16x32_bf16 v[62:65], v[136:139], v[208:211], v[62:65]
	v_mfma_f32_16x16x32_bf16 v[58:61], v[144:147], v[208:211], v[58:61]
	v_mfma_f32_16x16x32_bf16 v[46:49], v[136:139], v[216:219], v[46:49]
	v_mfma_f32_16x16x32_bf16 v[42:45], v[144:147], v[216:219], v[42:45]
	v_mfma_f32_16x16x32_bf16 v[30:33], v[136:139], v[224:227], v[30:33]
	v_mfma_f32_16x16x32_bf16 v[26:29], v[144:147], v[224:227], v[26:29]
	v_mfma_f32_16x16x32_bf16 v[14:17], v[136:139], v[242:245], v[14:17]
	v_mfma_f32_16x16x32_bf16 v[10:13], v[144:147], v[242:245], v[10:13]
	s_setprio 0
	s_setprio 1
	v_mfma_f32_16x16x32_bf16 v[54:57], v[156:159], v[204:207], v[54:57]
	v_mfma_f32_16x16x32_bf16 v[50:53], v[192:195], v[204:207], v[50:53]
	v_mfma_f32_16x16x32_bf16 v[38:41], v[156:159], v[212:215], v[38:41]
	v_mfma_f32_16x16x32_bf16 v[34:37], v[192:195], v[212:215], v[34:37]
	v_mfma_f32_16x16x32_bf16 v[22:25], v[156:159], v[220:223], v[22:25]
	v_mfma_f32_16x16x32_bf16 v[18:21], v[192:195], v[220:223], v[18:21]
	v_mfma_f32_16x16x32_bf16 v[6:9], v[156:159], v[238:241], v[6:9]
	v_mfma_f32_16x16x32_bf16 v[2:5], v[192:195], v[238:241], v[2:5]
	v_mfma_f32_16x16x32_bf16 v[54:57], v[162:165], v[208:211], v[54:57]
	v_mfma_f32_16x16x32_bf16 v[50:53], v[200:203], v[208:211], v[50:53]
	v_mfma_f32_16x16x32_bf16 v[38:41], v[162:165], v[216:219], v[38:41]
	v_mfma_f32_16x16x32_bf16 v[34:37], v[200:203], v[216:219], v[34:37]
	v_mfma_f32_16x16x32_bf16 v[22:25], v[162:165], v[224:227], v[22:25]
	v_mfma_f32_16x16x32_bf16 v[18:21], v[200:203], v[224:227], v[18:21]
	v_mfma_f32_16x16x32_bf16 v[6:9], v[162:165], v[242:245], v[6:9]
	v_mfma_f32_16x16x32_bf16 v[2:5], v[200:203], v[242:245], v[2:5]
	s_setprio 0
	s_barrier
	s_add_i32 s6, 0, 0x18000
	s_add_i32 s7, 0, 0x1c000
	v_add_u32_e32 v144, s6, v189
	v_add_u32_e32 v160, s7, v189
	ds_read_b128 v[132:135], v144
	ds_read_b128 v[136:139], v144 offset:1024
	ds_read_b128 v[140:143], v144 offset:2048
	ds_read_b128 v[144:147], v144 offset:3072
	ds_read_b128 v[156:159], v160
	ds_read_b128 v[162:165], v160 offset:1024
	ds_read_b128 v[192:195], v160 offset:2048
	ds_read_b128 v[200:203], v160 offset:3072
	s_add_u32 s4, s68, 0x40000
	s_addc_u32 s5, s69, 0
	v_lshl_add_u64 v[246:247], s[4:5], 0, v[98:99]
	s_add_i32 m0, s44, 0x4000
	ds_read_b128 v[204:207], v191 offset:32768
	ds_read_b128 v[208:211], v191 offset:33792
	ds_read_b128 v[212:215], v191 offset:34816
	ds_read_b128 v[216:219], v191 offset:35840
	ds_read_b128 v[220:223], v191 offset:36864
	ds_read_b128 v[224:227], v191 offset:37888
	ds_read_b128 v[238:241], v191 offset:38912
	ds_read_b128 v[242:245], v191 offset:39936
	global_load_lds_dwordx4 v[246:247], off
	v_lshl_add_u64 v[246:247], s[4:5], 0, v[150:151]
	s_add_i32 m0, s44, 0x6000
	s_nop 0
	global_load_lds_dwordx4 v[246:247], off
	s_waitcnt vmcnt(8)
	s_waitcnt lgkmcnt(0)
	s_setprio 1
	s_barrier
	v_mfma_f32_16x16x32_bf16 v[128:131], v[132:135], v[204:207], v[128:131]
	v_mfma_f32_16x16x32_bf16 v[124:127], v[140:143], v[204:207], v[124:127]
	v_mfma_f32_16x16x32_bf16 v[112:115], v[132:135], v[212:215], v[112:115]
	v_mfma_f32_16x16x32_bf16 v[108:111], v[140:143], v[212:215], v[108:111]
	v_mfma_f32_16x16x32_bf16 v[94:97], v[132:135], v[220:223], v[94:97]
	v_mfma_f32_16x16x32_bf16 v[90:93], v[140:143], v[220:223], v[90:93]
	v_mfma_f32_16x16x32_bf16 v[78:81], v[132:135], v[238:241], v[78:81]
	v_mfma_f32_16x16x32_bf16 v[74:77], v[140:143], v[238:241], v[74:77]
	v_mfma_f32_16x16x32_bf16 v[128:131], v[136:139], v[208:211], v[128:131]
	v_mfma_f32_16x16x32_bf16 v[124:127], v[144:147], v[208:211], v[124:127]
	v_mfma_f32_16x16x32_bf16 v[112:115], v[136:139], v[216:219], v[112:115]
	v_mfma_f32_16x16x32_bf16 v[108:111], v[144:147], v[216:219], v[108:111]
	v_mfma_f32_16x16x32_bf16 v[94:97], v[136:139], v[224:227], v[94:97]
	v_mfma_f32_16x16x32_bf16 v[90:93], v[144:147], v[224:227], v[90:93]
	v_mfma_f32_16x16x32_bf16 v[78:81], v[136:139], v[242:245], v[78:81]
	v_mfma_f32_16x16x32_bf16 v[74:77], v[144:147], v[242:245], v[74:77]
	s_setprio 0
	s_setprio 1
	v_mfma_f32_16x16x32_bf16 v[120:123], v[156:159], v[204:207], v[120:123]
	v_mfma_f32_16x16x32_bf16 v[116:119], v[192:195], v[204:207], v[116:119]
	v_mfma_f32_16x16x32_bf16 v[104:107], v[156:159], v[212:215], v[104:107]
	v_mfma_f32_16x16x32_bf16 v[100:103], v[192:195], v[212:215], v[100:103]
	v_mfma_f32_16x16x32_bf16 v[86:89], v[156:159], v[220:223], v[86:89]
	v_mfma_f32_16x16x32_bf16 v[82:85], v[192:195], v[220:223], v[82:85]
	v_mfma_f32_16x16x32_bf16 v[70:73], v[156:159], v[238:241], v[70:73]
	v_mfma_f32_16x16x32_bf16 v[66:69], v[192:195], v[238:241], v[66:69]
	v_mfma_f32_16x16x32_bf16 v[120:123], v[162:165], v[208:211], v[120:123]
	v_mfma_f32_16x16x32_bf16 v[116:119], v[200:203], v[208:211], v[116:119]
	v_mfma_f32_16x16x32_bf16 v[104:107], v[162:165], v[216:219], v[104:107]
	v_mfma_f32_16x16x32_bf16 v[100:103], v[200:203], v[216:219], v[100:103]
	v_mfma_f32_16x16x32_bf16 v[86:89], v[162:165], v[224:227], v[86:89]
	v_mfma_f32_16x16x32_bf16 v[82:85], v[200:203], v[224:227], v[82:85]
	v_mfma_f32_16x16x32_bf16 v[70:73], v[162:165], v[242:245], v[70:73]
	v_mfma_f32_16x16x32_bf16 v[66:69], v[200:203], v[242:245], v[66:69]
	s_setprio 0
	s_barrier
	s_add_i32 s4, s6, s70
	v_lshl_add_u64 v[166:167], v[166:167], 0, s[42:43]
	s_mov_b32 m0, s4
	ds_read_b128 v[204:207], v191 offset:49152
	ds_read_b128 v[208:211], v191 offset:50176
	ds_read_b128 v[212:215], v191 offset:51200
	ds_read_b128 v[216:219], v191 offset:52224
	ds_read_b128 v[220:223], v191 offset:53248
	ds_read_b128 v[224:227], v191 offset:54272
	ds_read_b128 v[238:241], v191 offset:55296
	ds_read_b128 v[242:245], v191 offset:56320
	global_load_lds_dwordx4 v[166:167], off
	s_add_i32 m0, s4, 0x2000
	s_add_u32 s4, s56, 0x40080
	v_lshl_add_u64 v[166:167], v[170:171], 0, s[42:43]
	s_addc_u32 s5, s57, 0
	s_add_i32 s6, s7, s70
	global_load_lds_dwordx4 v[166:167], off
	v_lshl_add_u64 v[166:167], s[4:5], 0, v[148:149]
	s_mov_b32 m0, s6
	s_nop 0
	global_load_lds_dwordx4 v[166:167], off
	v_lshl_add_u64 v[166:167], s[4:5], 0, v[152:153]
	s_add_i32 m0, s6, 0x2000
	s_nop 0
	global_load_lds_dwordx4 v[166:167], off
	v_lshl_add_u64 v[166:167], v[176:177], 0, s[42:43]
	s_add_i32 m0, s44, 0x8000
	s_nop 0
	global_load_lds_dwordx4 v[166:167], off
	v_lshl_add_u64 v[166:167], v[180:181], 0, s[42:43]
	s_add_i32 m0, s44, 0xa000
	s_nop 0
	global_load_lds_dwordx4 v[166:167], off
	s_waitcnt vmcnt(8)
	s_waitcnt lgkmcnt(0)
	s_setprio 1
	s_barrier
	v_mfma_f32_16x16x32_bf16 v[62:65], v[132:135], v[204:207], v[62:65]
	v_mfma_f32_16x16x32_bf16 v[58:61], v[140:143], v[204:207], v[58:61]
	v_mfma_f32_16x16x32_bf16 v[46:49], v[132:135], v[212:215], v[46:49]
	v_mfma_f32_16x16x32_bf16 v[42:45], v[140:143], v[212:215], v[42:45]
	v_mfma_f32_16x16x32_bf16 v[30:33], v[132:135], v[220:223], v[30:33]
	v_mfma_f32_16x16x32_bf16 v[26:29], v[140:143], v[220:223], v[26:29]
	v_mfma_f32_16x16x32_bf16 v[14:17], v[132:135], v[238:241], v[14:17]
	v_mfma_f32_16x16x32_bf16 v[10:13], v[140:143], v[238:241], v[10:13]
	v_mfma_f32_16x16x32_bf16 v[62:65], v[136:139], v[208:211], v[62:65]
	v_mfma_f32_16x16x32_bf16 v[58:61], v[144:147], v[208:211], v[58:61]
	v_mfma_f32_16x16x32_bf16 v[46:49], v[136:139], v[216:219], v[46:49]
	v_mfma_f32_16x16x32_bf16 v[42:45], v[144:147], v[216:219], v[42:45]
	v_mfma_f32_16x16x32_bf16 v[30:33], v[136:139], v[224:227], v[30:33]
	v_mfma_f32_16x16x32_bf16 v[26:29], v[144:147], v[224:227], v[26:29]
	v_mfma_f32_16x16x32_bf16 v[14:17], v[136:139], v[242:245], v[14:17]
	v_mfma_f32_16x16x32_bf16 v[10:13], v[144:147], v[242:245], v[10:13]
	s_setprio 0
	s_setprio 1
	v_mfma_f32_16x16x32_bf16 v[54:57], v[156:159], v[204:207], v[54:57]
	v_mfma_f32_16x16x32_bf16 v[50:53], v[192:195], v[204:207], v[50:53]
	v_mfma_f32_16x16x32_bf16 v[38:41], v[156:159], v[212:215], v[38:41]
	v_mfma_f32_16x16x32_bf16 v[34:37], v[192:195], v[212:215], v[34:37]
	v_mfma_f32_16x16x32_bf16 v[22:25], v[156:159], v[220:223], v[22:25]
	v_mfma_f32_16x16x32_bf16 v[18:21], v[192:195], v[220:223], v[18:21]
	v_mfma_f32_16x16x32_bf16 v[6:9], v[156:159], v[238:241], v[6:9]
	v_mfma_f32_16x16x32_bf16 v[2:5], v[192:195], v[238:241], v[2:5]
	v_mfma_f32_16x16x32_bf16 v[54:57], v[162:165], v[208:211], v[54:57]
	v_mfma_f32_16x16x32_bf16 v[50:53], v[200:203], v[208:211], v[50:53]
	v_mfma_f32_16x16x32_bf16 v[38:41], v[162:165], v[216:219], v[38:41]
	v_mfma_f32_16x16x32_bf16 v[34:37], v[200:203], v[216:219], v[34:37]
	v_mfma_f32_16x16x32_bf16 v[22:25], v[162:165], v[224:227], v[22:25]
	v_mfma_f32_16x16x32_bf16 v[18:21], v[200:203], v[224:227], v[18:21]
	v_mfma_f32_16x16x32_bf16 v[6:9], v[162:165], v[242:245], v[6:9]
	v_mfma_f32_16x16x32_bf16 v[2:5], v[200:203], v[242:245], v[2:5]
	s_setprio 0
	s_barrier
	s_add_i32 s92, s92, 2
	s_add_u32 s40, s40, 0x100
	s_addc_u32 s41, s41, 0
	s_add_u32 s90, s90, 0x100
	s_addc_u32 s91, s91, 0
	s_cmp_gt_u32 s92, 13
	s_cbranch_scc0 .LBB0_1011
	s_mov_b32 s100, 1
	s_and_b64 vcc, exec, s[0:1]
	s_cbranch_vccz .LBB0_1014
	s_lshl_b32 s4, s77, 8
	v_add_u32_e32 v162, s4, v188
	v_ashrrev_i32_e32 v163, 31, v162
	v_or_b32_e32 v180, 16, v162
	v_lshlrev_b64 v[132:133], 6, v[162:163]
	v_ashrrev_i32_e32 v181, 31, v180
	v_or_b32_e32 v176, 32, v162
	v_lshl_add_u64 v[132:133], v[154:155], 0, v[132:133]
	v_lshlrev_b64 v[134:135], 6, v[180:181]
	v_ashrrev_i32_e32 v177, 31, v176
	v_lshl_add_u64 v[134:135], v[154:155], 0, v[134:135]
	global_load_dwordx4 v[192:195], v[132:133], off
	global_load_dwordx4 v[200:203], v[134:135], off
	v_lshlrev_b64 v[132:133], 6, v[176:177]
	v_lshl_add_u64 v[132:133], v[154:155], 0, v[132:133]
	global_load_dwordx4 v[204:207], v[132:133], off
	v_or_b32_e32 v170, 48, v162
	v_ashrrev_i32_e32 v171, 31, v170
	v_lshlrev_b64 v[132:133], 6, v[170:171]
	v_lshl_add_u64 v[132:133], v[154:155], 0, v[132:133]
	global_load_dwordx4 v[208:211], v[132:133], off
	v_add_u32_e32 v166, 0x80, v162
	v_ashrrev_i32_e32 v167, 31, v166
	v_lshlrev_b64 v[132:133], 6, v[166:167]
	v_lshl_add_u64 v[132:133], v[154:155], 0, v[132:133]
	global_load_dwordx4 v[212:215], v[132:133], off
	v_add_u32_e32 v164, 0x90, v162
	v_and_b32_e32 v132, 64, v229
	v_ashrrev_i32_e32 v165, 31, v164
	v_add_u32_e32 v136, 64, v132
	v_lshlrev_b64 v[132:133], 6, v[164:165]
	v_lshl_add_u64 v[132:133], v[154:155], 0, v[132:133]
	global_load_dwordx4 v[216:219], v[132:133], off
	v_add_u32_e32 v158, 0xa0, v162
	v_ashrrev_i32_e32 v159, 31, v158
	v_add_u32_e32 v156, 0xb0, v162
	v_lshlrev_b64 v[132:133], 6, v[158:159]
	v_ashrrev_i32_e32 v157, 31, v156
	v_lshl_add_u64 v[132:133], v[154:155], 0, v[132:133]
	global_load_dwordx4 v[220:223], v[132:133], off
	v_lshlrev_b64 v[132:133], 6, v[156:157]
	v_lshl_add_u64 v[132:133], v[154:155], 0, v[132:133]
	global_load_dwordx4 v[224:227], v[132:133], off
	s_addk_i32 s4, 0xc000
	s_lshr_b32 s4, s4, 12
	s_ashr_i32 s5, s77, 5
	s_add_i32 s4, s4, 2
	s_cmp_lt_i32 s77, 64
	s_cselect_b32 s4, s5, s4
	s_ashr_i32 s5, s4, 31
	v_xor_b32_e32 v134, 16, v229
	s_lshl_b64 s[4:5], s[4:5], 14
	v_lshl_or_b32 v238, s79, 8, v190
	v_xor_b32_e32 v135, 32, v229
	v_cmp_lt_i32_e32 vcc, v134, v136
	s_add_u32 s4, s71, s4
	v_ashrrev_i32_e32 v239, 31, v238
	v_cndmask_b32_e32 v134, v229, v134, vcc
	v_cmp_lt_i32_e32 vcc, v135, v136
	s_addc_u32 s5, s74, s5
	v_lshl_add_u64 v[136:137], v[238:239], 2, s[4:5]
	v_cndmask_b32_e32 v135, v229, v135, vcc
	v_lshlrev_b32_e32 v160, 2, v134
	v_lshlrev_b32_e32 v168, 2, v135
	global_load_dwordx4 v[140:143], v[136:137], off offset:16
	global_load_dwordx4 v[144:147], v[136:137], off
	global_load_dwordx4 v[132:135], v[136:137], off offset:528
	s_nop 0
	global_load_dwordx4 v[136:139], v[136:137], off offset:512
	s_barrier
	s_branch .Lmy_g3_afterload

.Lmy_g3_afterload:
	s_andn2_b64 vcc, exec, s[36:37]
	s_mov_b64 s[36:37], -1
	s_waitcnt vmcnt(0)
	v_mov_b32_e32 v240, v193
	v_mov_b32_e32 v241, v194
	v_mov_b32_e32 v193, v195
	v_pk_add_f32 v[192:193], v[240:241], v[192:193]
	v_mov_b32_e32 v194, v201
	v_mov_b32_e32 v195, v202
	v_mov_b32_e32 v201, v203
	v_add_f32_e32 v172, v192, v193
	v_pk_add_f32 v[192:193], v[194:195], v[200:201]
	v_mov_b32_e32 v202, v205
	v_mov_b32_e32 v203, v206
	v_mov_b32_e32 v205, v207
	ds_bpermute_b32 v174, v160, v172
	v_add_f32_e32 v178, v192, v193
	v_pk_add_f32 v[194:195], v[202:203], v[204:205]
	ds_bpermute_b32 v192, v160, v178
	v_add_f32_e32 v182, v194, v195
	ds_bpermute_b32 v194, v160, v182
	s_waitcnt lgkmcnt(2)
	v_add_f32_e32 v172, v172, v174
	ds_bpermute_b32 v174, v168, v172
	s_waitcnt lgkmcnt(2)
	v_add_f32_e32 v178, v178, v192
	v_mov_b32_e32 v206, v209
	v_mov_b32_e32 v207, v210
	v_mov_b32_e32 v209, v211
	ds_bpermute_b32 v192, v168, v178
	v_pk_add_f32 v[200:201], v[206:207], v[208:209]
	s_waitcnt lgkmcnt(2)
	v_add_f32_e32 v182, v182, v194
	v_add_f32_e32 v193, v200, v201
	ds_bpermute_b32 v200, v168, v182
	ds_bpermute_b32 v195, v160, v193
	s_waitcnt lgkmcnt(3)
	v_add_f32_e32 v172, v172, v174
	v_fmamk_f32 v172, v172, 0x3a800000, v1
	s_waitcnt lgkmcnt(2)
	v_add_f32_e32 v174, v178, v192
	v_rsq_f32_e32 v192, v172
	v_fmamk_f32 v172, v174, 0x3a800000, v1
	v_rsq_f32_e32 v194, v172
	s_waitcnt lgkmcnt(1)
	v_add_f32_e32 v172, v182, v200
	v_mov_b32_e32 v200, v213
	v_mov_b32_e32 v201, v214
	v_mov_b32_e32 v213, v215
	v_pk_add_f32 v[200:201], v[200:201], v[212:213]
	s_waitcnt lgkmcnt(0)
	v_add_f32_e32 v174, v193, v195
	v_add_f32_e32 v193, v200, v201
	ds_bpermute_b32 v178, v168, v174
	ds_bpermute_b32 v195, v160, v193
	v_fmamk_f32 v172, v172, 0x3a800000, v1
	v_rsq_f32_e32 v182, v172
	v_mov_b32_e32 v200, v217
	s_waitcnt lgkmcnt(1)
	v_add_f32_e32 v172, v174, v178
	s_waitcnt lgkmcnt(0)
	v_add_f32_e32 v174, v193, v195
	v_mov_b32_e32 v201, v218
	v_mov_b32_e32 v217, v219
	ds_bpermute_b32 v193, v168, v174
	v_pk_add_f32 v[200:201], v[200:201], v[216:217]
	v_fmamk_f32 v172, v172, 0x3a800000, v1
	v_add_f32_e32 v195, v200, v201
	ds_bpermute_b32 v200, v160, v195
	v_rsq_f32_e32 v178, v172
	s_waitcnt lgkmcnt(1)
	v_add_f32_e32 v172, v174, v193
	v_fmamk_f32 v172, v172, 0x3a800000, v1
	v_rsq_f32_e32 v174, v172
	s_waitcnt lgkmcnt(0)
	v_add_f32_e32 v172, v195, v200
	v_mov_b32_e32 v200, v221
	v_mov_b32_e32 v201, v222
	v_mov_b32_e32 v221, v223
	v_pk_add_f32 v[200:201], v[200:201], v[220:221]
	ds_bpermute_b32 v193, v168, v172
	v_add_f32_e32 v195, v200, v201
	v_mov_b32_e32 v200, v225
	v_mov_b32_e32 v201, v226
	v_mov_b32_e32 v225, v227
	v_pk_add_f32 v[200:201], v[200:201], v[224:225]
	ds_bpermute_b32 v202, v160, v195
	v_add_f32_e32 v200, v200, v201
	ds_bpermute_b32 v160, v160, v200
	s_waitcnt lgkmcnt(2)
	v_add_f32_e32 v172, v172, v193
	v_pk_fma_f32 v[94:95], v[94:95], v[182:183], v[144:145] op_sel_hi:[1,0,1]
	s_waitcnt lgkmcnt(1)
	v_add_f32_e32 v193, v195, v202
	ds_bpermute_b32 v195, v168, v193
	s_waitcnt lgkmcnt(1)
	v_add_f32_e32 v160, v200, v160
	ds_bpermute_b32 v200, v168, v160
	v_pk_fma_f32 v[128:129], v[128:129], v[192:193], v[144:145] op_sel_hi:[1,0,1]
	v_pk_fma_f32 v[130:131], v[130:131], v[192:193], v[146:147] op_sel_hi:[1,0,1]
	v_pk_fma_f32 v[126:127], v[126:127], v[192:193], v[142:143] op_sel_hi:[1,0,1]
	v_pk_fma_f32 v[124:125], v[124:125], v[192:193], v[140:141] op_sel_hi:[1,0,1]
	v_max_f32_e32 v128, 0, v128
	v_max_f32_e32 v129, 0, v129
	s_waitcnt lgkmcnt(0)
	v_add_f32_e32 v160, v160, v200
	v_lshlrev_b64 v[200:201], 13, v[162:163]
	v_max_f32_e32 v124, 0, v124
	v_max_f32_e32 v125, 0, v125
	v_max_f32_e32 v130, 0, v130
	v_max_f32_e32 v126, 0, v126
	v_max_f32_e32 v131, 0, v131
	v_max_f32_e32 v127, 0, v127
	v_pk_mul_f32 v[128:129], v[128:129], v[128:129]
	v_lshlrev_b64 v[162:163], 1, v[238:239]
	v_pk_mul_f32 v[130:131], v[130:131], v[130:131]
	v_pk_mul_f32 v[202:203], v[126:127], v[126:127]
	v_pk_mul_f32 v[126:127], v[124:125], v[124:125]
	v_cvt_pk_bf16_f32 v124, v128, v129
	v_lshl_add_u64 v[128:129], s[24:25], 0, v[200:201]
	v_pk_fma_f32 v[122:123], v[122:123], v[192:193], v[138:139] op_sel_hi:[1,0,1]
	v_pk_fma_f32 v[120:121], v[120:121], v[192:193], v[136:137] op_sel_hi:[1,0,1]
	v_pk_fma_f32 v[118:119], v[118:119], v[192:193], v[134:135] op_sel_hi:[1,0,1]
	v_pk_fma_f32 v[116:117], v[116:117], v[192:193], v[132:133] op_sel_hi:[1,0,1]
	v_cvt_pk_bf16_f32 v125, v130, v131
	v_cvt_pk_bf16_f32 v126, v126, v127
	v_cvt_pk_bf16_f32 v127, v202, v203
	v_lshl_add_u64 v[128:129], v[128:129], 0, v[162:163]
	v_max_f32_e32 v120, 0, v120
	v_max_f32_e32 v116, 0, v116
	v_max_f32_e32 v121, 0, v121
	v_max_f32_e32 v117, 0, v117
	v_max_f32_e32 v122, 0, v122
	v_max_f32_e32 v118, 0, v118
	v_max_f32_e32 v123, 0, v123
	v_max_f32_e32 v119, 0, v119
	s_cbranch_vccnz .Lmy_wt_g3_0
	global_store_dwordx4 v[128:129], v[124:127], off
